# grid barrier: non-leader workgroups invalidate their L1 before spinning on the release instead of after it (leader XCD invalidate unchanged)
# speedup vs baseline: 1.0152x; 1.0104x over previous
.LBB0_942:
	s_or_b64 exec, exec, s[6:7]
	v_cvt_f32_u32_e32 v5, v3
	s_waitcnt vmcnt(0)
	v_readfirstlane_b32 s4, v4
	v_sub_u32_e32 v4, 0, v3
	v_rcp_iflag_f32_e32 v5, v5
	v_add_u32_e32 v6, s4, v0
	v_mul_f32_e32 v5, 0x4f7ffffe, v5
	v_cvt_u32_f32_e32 v5, v5
	v_mul_lo_u32 v0, v4, v5
	v_mul_hi_u32 v0, v5, v0
	v_add_u32_e32 v0, v5, v0
	v_mul_hi_u32 v0, v6, v0
	v_mul_lo_u32 v4, v0, v3
	v_sub_u32_e32 v4, v6, v4
	v_add_u32_e32 v5, 1, v0
	v_cmp_ge_u32_e32 vcc, v4, v3
	s_nop 1
	v_cndmask_b32_e32 v0, v0, v5, vcc
	v_sub_u32_e32 v5, v4, v3
	v_cndmask_b32_e32 v4, v4, v5, vcc
	v_add_u32_e32 v5, 1, v0
	v_cmp_ge_u32_e32 vcc, v4, v3
	v_add_u32_e32 v4, 1, v6
	s_nop 0
	v_cndmask_b32_e32 v0, v0, v5, vcc
	v_mul_lo_u32 v5, v3, v0
	v_add_u32_e32 v3, v5, v3
	v_cmp_ne_u32_e32 vcc, v4, v3
	s_and_saveexec_b64 s[4:5], vcc
	s_xor_b64 s[4:5], exec, s[4:5]
	s_cbranch_execz .LBB0_957
	s_waitcnt lgkmcnt(0)
	buffer_inv sc1
	global_load_dword v2, v254, s[2:3] offset:1024 sc1
	s_add_u32 s10, s2, 0x2400
	s_addc_u32 s11, s3, 0
	s_waitcnt vmcnt(0)
	v_cmp_eq_u32_e32 vcc, v2, v0
	s_and_saveexec_b64 s[6:7], vcc
	s_cbranch_execz .LBB0_956
	s_add_u32 s8, s54, 0x1efc0200
	s_addc_u32 s9, s55, 0
	s_mov_b32 s22, 1
	s_mov_b64 s[12:13], 0
	s_branch .LBB0_946

.LBB0_956:
	s_or_b64 exec, exec, s[6:7]
	s_waitcnt vmcnt(0)
	s_waitcnt vmcnt(0)
